# code placement: in_proj layers 0-2 K-loop and its peeled first trip shifted by 4 bytes (one s_nop 0 before the peeled trip, one after the loop)
# speedup vs baseline: 1.0066x; 1.0061x over previous
.LBB0_313:
	s_ashr_i32 s57, s56, 31
	s_lshl_b64 s[34:35], s[56:57], 19
	s_add_u32 s70, s26, s34
	s_addc_u32 s71, s27, s35
	s_and_b64 s[34:35], exec, s[12:13]
	s_cselect_b32 s57, s11, s71
	s_cselect_b32 s66, s10, s70
	s_ashr_i32 s63, s62, 31
	s_lshl_b64 s[34:35], s[62:63], 19
	s_add_u32 s72, s28, s34
	s_addc_u32 s73, s29, s35
	s_and_b64 s[34:35], exec, s[12:13]
	s_cselect_b32 s63, s9, s73
	s_cselect_b32 s90, s8, s72
	s_lshl_b32 s34, s56, 4
	s_ashr_i32 s35, s34, 31
	s_cmp_lt_i32 s56, 64
	s_cselect_b32 s91, 32, 0x100
	s_or_b64 s[12:13], s[12:13], s[46:47]
	s_lshl_b64 s[34:35], s[34:35], 2
	s_add_u32 s74, s61, s34
	s_addc_u32 s75, s55, s35
	s_mov_b32 s89, 0
	s_waitcnt vmcnt(0)
	s_nop 0

.LBB0_343:
	s_nop 0
	s_and_b64 vcc, exec, s[52:53]
	s_cbranch_vccz .LBB0_347
	s_barrier
	s_cmp_lt_i32 s87, 16
	s_mov_b64 s[8:9], -1
	s_cbranch_scc1 .LBB0_348
